# speedup vs baseline: 1.0332x; 1.0318x over previous
; DI int my_tid() { int t = threadIdx.x; asm volatile("" : "+v"(t)); return t; }
; DI void phase_mixers(int l_, unsigned* ctr, LAS unsigned char* lds) {
;     ...
;   for (;;) {
;     __syncthreads();
;     if (my_tid() == 0) *slot = nxt;
;     __syncthreads();
;     const int it = __builtin_amdgcn_readfirstlane(*slot);
;     if (it >= NIT) break;
;     if (my_tid() == 0) nxt = (int)__hip_atomic_fetch_add(ctr, 1u, __ATOMIC_RELAXED, __HIP_MEMORY_SCOPE_AGENT);
;     int r = it; { int lv = l; asm volatile("" : "+v"(lv)); l = __builtin_amdgcn_readfirstlane(lv); }
;     const __attribute__((address_space(4))) void* kpi = (const __attribute__((address_space(4))) void*)__builtin_amdgcn_kernarg_segment_ptr();
;     asm volatile("" : "+s"(kpi));
;     CP& p = *(CP*)kpi;
;     if (r < N_MEM) { mix_mem(p, l, r, lds); continue; } r -= N_MEM;
;     if (r < N_SB) { mix_sb(p, l, r, lds); continue; } r -= N_SB;
;     if (r < N_G) { mix_gmlp(p, l, r, lds); continue; } r -= N_G;
;     if (r < N_C) { mix_conv(p, l, r, lds); continue; }
.LBB0_119:
	v_mov_b32_e32 v1, v144
	s_waitcnt vmcnt(0) lgkmcnt(0)
	s_barrier
	s_nop 0
	v_cmp_eq_u32_e32 vcc, 0, v1
	s_and_saveexec_b64 s[8:9], vcc
	v_mov_b32_e32 v1, s95
	ds_write_b32 v1, v134
	s_or_b64 exec, exec, s[8:9]
	v_mov_b32_e32 v1, s95
	s_waitcnt lgkmcnt(0)
	s_barrier
	ds_read_b32 v1, v1
	s_waitcnt lgkmcnt(0)
	v_readfirstlane_b32 s74, v1
	s_cmpk_gt_i32 s74, 0x4d0
	s_cbranch_scc1 .LBB0_134
	s_movk_i32 s0, 0xfe6f
	s_cmpk_lt_i32 s74, 0x191
	s_cselect_b32 s0, 0x237, s0
	s_cmpk_lt_i32 s74, 0x109
	s_cselect_b32 s0, 0x3c8, s0
	s_add_i32 s74, s74, s0
	v_mov_b32_e32 v1, v144
	s_nop 0
	v_cmp_eq_u32_e32 vcc, 0, v1
	s_and_saveexec_b64 s[8:9], vcc
	s_cbranch_execz .LBB0_126
	s_mov_b64 s[12:13], exec
	v_mbcnt_lo_u32_b32 v1, s12, 0
	v_mbcnt_hi_u32_b32 v1, s13, v1
	v_cmp_eq_u32_e32 vcc, 0, v1
	s_and_saveexec_b64 s[10:11], vcc
	s_cbranch_execz .LBB0_125
	s_bcnt1_i32_b64 s0, s[12:13]
	v_mov_b32_e32 v2, s0
	global_atomic_add v2, v147, v2, s[62:63] sc0
